# adds P6 output-projection epilogue with batched loads and P3 sample-mLSTM batched staging on top of v18
# baseline (speedup 1.0000x reference)
; __device__ __forceinline__ float bfv(bf16 v) { return __uint_as_float((unsigned)v << 16); }
; template <int MASK> __device__ __forceinline__ void phase3(const Args& a, LAS unsigned char* lds, int tid, int wave, int lane, int vcu, int G) {
;     ...
;             { const int b = ub >> 2, hd = ub & 3;
;                 __syncthreads();
;                 for (int i = tid; i < 3072; i += NTHREADS) { const int which = i >> 10, t = (i >> 7) & 7, d = i & 127; const size_t R = NP + 8 * b + t;
;                     QS[i] = which == 0 ? bfv(P1[R * P1W + C_MQ + hd * 128 + d]) : which == 1 ? bfv(P1[R * P1W + C_MK + hd * 128 + d]) : bfv(PT[(size_t)(R_MVT + hd * 128 + d) * MT + R]); }
.LBB0_700:
	s_and_b32 s37, s46, 3
	s_mov_b32 s4, s94
	s_lshl_b32 s94, s37, 7
	v_or_b32_e32 v2, s94, v108
	s_lshl_b32 s2, s46, 1
	v_mul_u32_u24_e32 v2, 0x4400, v2
	s_and_b32 s48, s2, -8
	v_lshlrev_b32_e32 v94, 1, v2
	s_lshl_b32 s52, s37, 8
	s_add_i32 s54, s48, 0x4000
	s_waitcnt lgkmcnt(0)
	v_lshl_add_u64 v[2:3], s[58:59], 0, v[94:95]
	v_lshl_add_u64 v[4:5], v[138:139], 0, s[52:53]
	v_add_u32_e32 v170, s54, v223
	v_add_u32_e32 v171, 4, v170
	s_mov_b64 s[88:89], 0x800
	v_mad_i64_i32 v[172:173], s[2:3], v170, s95, v[4:5]
	v_mad_i64_i32 v[174:175], s[2:3], v171, s95, v[4:5]
	global_load_ushort v182, v[172:173], off offset:2048
	global_load_ushort v183, v[174:175], off offset:2048
	v_lshl_add_u64 v[172:173], v[172:173], 0, s[88:89]
	v_lshl_add_u64 v[174:175], v[174:175], 0, s[88:89]
	global_load_ushort v184, v[172:173], off offset:2048
	global_load_ushort v185, v[174:175], off offset:2048
	v_mad_u64_u32 v[176:177], s[2:3], v170, 2, v[2:3]
	v_mad_u64_u32 v[178:179], s[2:3], v171, 2, v[2:3]
	global_load_ushort v186, v[176:177], off
	global_load_ushort v187, v[178:179], off
	s_barrier
	s_waitcnt vmcnt(5)
	v_lshlrev_b32_e32 v182, 16, v182
	ds_write_b32 v216, v182
	s_waitcnt vmcnt(4)
	v_lshlrev_b32_e32 v183, 16, v183
	ds_write_b32 v216, v183 offset:2048
	s_waitcnt vmcnt(3)
	v_lshlrev_b32_e32 v184, 16, v184
	ds_write_b32 v216, v184 offset:4096
	s_waitcnt vmcnt(2)
	v_lshlrev_b32_e32 v185, 16, v185
	ds_write_b32 v216, v185 offset:6144
	s_waitcnt vmcnt(1)
	v_lshlrev_b32_e32 v186, 16, v186
	ds_write_b32 v216, v186 offset:8192
	s_waitcnt vmcnt(0)
	v_lshlrev_b32_e32 v187, 16, v187
	ds_write_b32 v216, v187 offset:10240
	s_and_saveexec_b64 s[88:89], s[30:31]
	s_cbranch_execz .LBB0_712
; template <int MASK> __device__ __forceinline__ void phase3(const Args& a, LAS unsigned char* lds, int tid, int wave, int lane, int vcu, int G) {
;     ...
;                 if (tid == 0) {
;                     const float m0 = a.in[6][b * 4 + hd]; float F = 0.f, cm = m0; float bb[8];
; #pragma unroll
;                     for (int t = 0; t < 8; ++t) { const size_t R = NP + 8 * b + t; F += LF[R * 4 + hd]; bb[t] = IG[R * 4 + hd] - F; cm = fmaxf(cm, bb[t]);
;                         SC[t] = F; SC[8 + t] = bb[t]; SC[16 + t] = cm; SC[24 + t] = __expf(m0 - cm); SC[32 + t] = F + cm; }
; #pragma unroll
;                     for (int s = 0; s < 8; ++s) SC[40 + s] = __expf(bb[s] - cm);
;                     SC[48] = __expf(m0 - cm); SC[49] = F + cm;
;                 }
	s_ashr_i32 s47, s46, 31
	v_readlane_b32 s8, v253, 11
	s_lshl_b64 s[2:3], s[46:47], 2
	v_readlane_b32 s20, v253, 23
	v_readlane_b32 s21, v253, 24
	s_add_u32 s2, s20, s2
	s_addc_u32 s3, s21, s3
	s_ashr_i32 s55, s54, 31
	global_load_dword v30, v95, s[2:3]
	s_lshl_b64 s[2:3], s[54:55], 4
	s_lshl_b32 s47, s37, 2
	s_or_b32 s2, s2, s47
	s_add_u32 s68, s78, s2
	s_addc_u32 s69, s79, s3
	s_add_u32 s2, s74, s2
	s_addc_u32 s3, s75, s3
	s_ashr_i32 s49, s48, 31
	s_lshl_b64 s[90:91], s[48:49], 4
	s_or_b32 s47, s90, s47
	s_add_u32 s49, s47, 0x40010
	s_addc_u32 s52, s91, 0
	global_load_dword v8, v95, s[68:69]
	global_load_dword v3, v95, s[2:3]
	s_add_u32 s2, s78, s49
	s_addc_u32 s3, s79, s52
	global_load_dword v9, v95, s[2:3]
	s_add_u32 s2, s74, s49
	s_addc_u32 s3, s75, s52
	s_add_u32 s49, s47, 0x40020
	s_addc_u32 s52, s91, 0
	global_load_dword v4, v95, s[2:3]
	s_add_u32 s2, s78, s49
	s_addc_u32 s3, s79, s52
	global_load_dword v10, v95, s[2:3]
	s_add_u32 s2, s74, s49
	s_addc_u32 s3, s75, s52
	s_add_u32 s49, s47, 0x40030
	s_addc_u32 s52, s91, 0
	global_load_dword v5, v95, s[2:3]
	s_add_u32 s2, s78, s49
	s_addc_u32 s3, s79, s52
	global_load_dword v11, v95, s[2:3]
	s_add_u32 s2, s74, s49
	s_addc_u32 s3, s75, s52
	s_add_u32 s49, s47, 0x40040
	s_addc_u32 s52, s91, 0
	global_load_dword v6, v95, s[2:3]
	s_add_u32 s2, s78, s49
	s_addc_u32 s3, s79, s52
	global_load_dword v18, v95, s[2:3]
	s_add_u32 s2, s74, s49
	s_addc_u32 s3, s75, s52
	s_add_u32 s49, s47, 0x40050
	s_addc_u32 s52, s91, 0
	global_load_dword v7, v95, s[2:3]
	s_add_u32 s2, s78, s49
	s_addc_u32 s3, s79, s52
	global_load_dword v19, v95, s[2:3]
	s_add_u32 s2, s74, s49
	s_addc_u32 s3, s75, s52
	s_add_u32 s49, s47, 0x40060
	s_addc_u32 s52, s91, 0
	global_load_dword v12, v95, s[2:3]
	s_add_u32 s2, s78, s49
	s_addc_u32 s3, s79, s52
	global_load_dword v20, v95, s[2:3]
	s_add_u32 s2, s74, s49
	s_addc_u32 s3, s75, s52
	s_add_u32 s47, s47, 0x40070
	s_addc_u32 s49, s91, 0
	global_load_dword v13, v95, s[2:3]
	s_add_u32 s2, s78, s47
	s_addc_u32 s3, s79, s49
	global_load_dword v2, v95, s[2:3]
	s_add_u32 s2, s74, s47
	s_addc_u32 s3, s75, s49
	global_load_dword v31, v95, s[2:3]
	v_readlane_b32 s2, v254, 37
	v_readlane_b32 s10, v253, 13
	v_readlane_b32 s11, v253, 14
	v_mov_b32_e32 v22, s2
	v_readlane_b32 s2, v254, 39
	v_readlane_b32 s12, v253, 15
	v_readlane_b32 s13, v253, 16
	v_mov_b32_e32 v24, s2
	v_readlane_b32 s2, v254, 41
	v_readlane_b32 s14, v253, 17
	v_readlane_b32 s15, v253, 18
	v_mov_b32_e32 v26, s2
	s_waitcnt vmcnt(16)
	v_max_f32_e32 v33, v30, v30
	v_readlane_b32 s2, v254, 43
	v_readlane_b32 s16, v253, 19
	v_readlane_b32 s17, v253, 20
	v_mov_b32_e32 v32, s2
	v_readlane_b32 s18, v253, 21
	s_movk_i32 s18, 0x3000
	s_movk_i32 s17, 0x2000
	s_movk_i32 s16, 0x4000
	s_mov_b32 s15, s38
	s_mov_b32 s14, s28
	s_mov_b32 s13, s36
	s_waitcnt vmcnt(15)
	v_add_f32_e32 v8, 0, v8
	v_mov_b32_e32 v21, v8
	s_mov_b32 s12, s73
	s_mov_b32 s11, s72
	s_waitcnt vmcnt(13)
	v_add_f32_e32 v9, v8, v9
	v_mov_b32_e32 v14, v9
	s_mov_b32 s10, s67
	v_readlane_b32 s9, v253, 12
	v_readlane_b32 s19, v253, 22
	v_readlane_b32 s22, v253, 25
	v_readlane_b32 s23, v253, 26
	s_waitcnt vmcnt(11)
	v_add_f32_e32 v15, v9, v10
	v_mov_b32_e32 v10, v15
	s_waitcnt vmcnt(10)
	v_pk_add_f32 v[16:17], v[4:5], v[14:15] neg_lo:[0,1] neg_hi:[0,1]
	ds_write2_b32 v22, v16, v17 offset1:1
	s_waitcnt vmcnt(9)
	v_add_f32_e32 v11, v15, v11
	v_mov_b32_e32 v14, v11
	ds_write_b128 v95, v[8:11] offset:12288
	s_waitcnt vmcnt(7)
	v_add_f32_e32 v15, v11, v18
	v_mov_b32_e32 v18, v15
	v_mov_b32_e32 v4, v15
	s_waitcnt vmcnt(6)
	v_pk_add_f32 v[22:23], v[6:7], v[14:15] neg_lo:[0,1] neg_hi:[0,1]
	ds_write2_b32 v24, v22, v23 offset1:1
	s_waitcnt vmcnt(5)
	v_add_f32_e32 v14, v15, v19
	v_mov_b32_e32 v5, v14
	v_mov_b32_e32 v19, v14
	s_waitcnt vmcnt(3)
	v_add_f32_e32 v20, v14, v20
	v_mov_b32_e32 v15, v20
	v_mov_b32_e32 v6, v20
	s_waitcnt vmcnt(2)
	v_pk_add_f32 v[24:25], v[12:13], v[14:15] neg_lo:[0,1] neg_hi:[0,1]
	ds_write_b96 v95, v[4:6] offset:12304
	ds_write2_b32 v26, v24, v25 offset1:1
	s_waitcnt vmcnt(1)
	v_pk_add_f32 v[28:29], v[2:3], v[20:21] neg_lo:[0,1] neg_hi:[0,1]
	v_pk_add_f32 v[26:27], v[2:3], v[20:21]
	v_max_f32_e32 v2, v33, v29
	v_sub_f32_e32 v4, v30, v2
	v_max_f32_e32 v3, v2, v16
	v_mul_f32_e32 v5, 0x3fb8aa3b, v4
	v_max_f32_e32 v4, v3, v17
	v_sub_f32_e32 v13, v30, v3
	v_exp_f32_e32 v12, v5
	v_max_f32_e32 v5, v4, v22
	v_pk_add_f32 v[6:7], v[8:9], v[2:3]
	v_mul_f32_e32 v8, 0x3fb8aa3b, v13
	v_sub_f32_e32 v9, v30, v4
	ds_write_b128 v95, v[2:5] offset:12352
	v_sub_f32_e32 v3, v30, v5
	v_max_f32_e32 v2, v5, v23
	v_exp_f32_e32 v13, v8
	v_mul_f32_e32 v14, 0x3fb8aa3b, v9
	v_pk_add_f32 v[8:9], v[10:11], v[4:5]
	v_mul_f32_e32 v4, 0x3fb8aa3b, v3
	v_sub_f32_e32 v5, v30, v2
	v_max_f32_e32 v3, v2, v24
	s_waitcnt vmcnt(0)
	v_sub_f32_e32 v27, v31, v26
	v_exp_f32_e32 v15, v4
	v_mul_f32_e32 v5, 0x3fb8aa3b, v5
	v_max_f32_e32 v4, v3, v25
	v_exp_f32_e32 v14, v14
	ds_write_b128 v95, v[6:9] offset:12416
	v_exp_f32_e32 v8, v5
	v_max_f32_e32 v5, v4, v27
	v_sub_f32_e32 v9, v30, v3
	v_sub_f32_e32 v10, v30, v4
	v_sub_f32_e32 v11, v30, v5
	v_mul_f32_e32 v9, 0x3fb8aa3b, v9
	v_mul_f32_e32 v10, 0x3fb8aa3b, v10
	v_mul_f32_e32 v11, 0x3fb8aa3b, v11
	v_exp_f32_e32 v9, v9
	v_exp_f32_e32 v10, v10
	v_exp_f32_e32 v11, v11
	v_pk_add_f32 v[6:7], v[18:19], v[2:3]
	ds_write_b128 v95, v[12:15] offset:12384
	ds_write2_b32 v32, v26, v29 offset1:1
	ds_write_b32 v95, v27 offset:12348
	ds_write_b128 v95, v[2:5] offset:12368
	ds_write_b128 v95, v[8:11] offset:12400
	v_sub_f32_e32 v2, v29, v5
	v_mul_f32_e32 v2, 0x3fb8aa3b, v2
	v_exp_f32_e32 v12, v2
	v_sub_f32_e32 v2, v16, v5
	v_mul_f32_e32 v2, 0x3fb8aa3b, v2
	v_exp_f32_e32 v13, v2
	v_sub_f32_e32 v2, v17, v5
	v_mul_f32_e32 v2, 0x3fb8aa3b, v2
	v_exp_f32_e32 v14, v2
	v_sub_f32_e32 v2, v22, v5
	v_mul_f32_e32 v2, 0x3fb8aa3b, v2
	v_exp_f32_e32 v15, v2
	v_sub_f32_e32 v2, v23, v5
	v_mul_f32_e32 v2, 0x3fb8aa3b, v2
	v_exp_f32_e32 v16, v2
	v_sub_f32_e32 v2, v24, v5
	v_mul_f32_e32 v2, 0x3fb8aa3b, v2
	v_exp_f32_e32 v17, v2
	v_sub_f32_e32 v2, v25, v5
	v_mul_f32_e32 v2, 0x3fb8aa3b, v2
	v_exp_f32_e32 v18, v2
	v_sub_f32_e32 v2, v27, v5
	v_mul_f32_e32 v2, 0x3fb8aa3b, v2
	v_mov_b32_e32 v21, v26
	v_exp_f32_e32 v19, v2
	v_pk_add_f32 v[8:9], v[20:21], v[4:5]
	ds_write_b128 v95, v[6:9] offset:12432
	ds_write_b128 v95, v[12:15] offset:12448
	ds_write_b128 v95, v[16:19] offset:12464
	v_mov_b32_e32 v8, v11
	ds_write_b64 v95, v[8:9] offset:12480

;     __device__ __forceinline__ void operator()(const pg8::f32x4 (&acc)[2][2][4][2], const pg8::Unit& u, int wr, int wc, int fr, int fq) const {
;         const int row0 = u.pm * 256 + wr * 64 + fr, colw = u.pn * 256 + wc * 32 + 8 * fq;
; #pragma unroll
;         for (int ai = 0; ai < 2; ++ai)
; #pragma unroll
;             for (int m = 0; m < 4; ++m) {
;                 const int r = row0 + ai * 128 + m * 16;
;                 const int brow = r < NP ? 0 : 1 + ((r - NP) >> 3);
;                 const float* gt = mod + (size_t)brow * 6144 + 2048;
;                 const f32x4 s4 = *(const f32x4*)(SSM + (size_t)r * 4);
;                 const float ss = (s4[0] + s4[1]) + (s4[2] + s4[3]);
;                 const float rstd = 1.0f / sqrtf(ss * (1.f / 512.f) + EPS);
;                 const float* base = r < NP ? xp + (size_t)r * DM : xs + (size_t)(r - NP) * DM;
; #pragma unroll
;                 for (int bj = 0; bj < 2; ++bj) {
;                     const int col = colw + bj * 128;
;                     const f32x4 x0 = *(const f32x4*)(base + col), x1v = *(const f32x4*)(base + col + 4), g0 = *(const f32x4*)(gt + col) * rstd, g1 = *(const f32x4*)(gt + col + 4) * rstd;
.LBB0_1150:
	s_cmp_lg_u32 s68, 0
	v_lshl_add_u32 v4, s2, 8, v169
	s_cselect_b64 s[36:37], -1, 0
	v_or_b32_e32 v152, 16, v4
	v_or_b32_e32 v150, 32, v4
	s_and_b64 vcc, exec, s[36:37]
	v_ashrrev_i32_e32 v5, 31, v4
	v_ashrrev_i32_e32 v153, 31, v152
	v_ashrrev_i32_e32 v151, 31, v150
	v_or_b32_e32 v148, 48, v4
	v_add_u32_e32 v146, 0x80, v4
	s_cbranch_vccz .LBB0_1162
	v_lshl_or_b32 v191, s3, 8, v187
	v_lshlrev_b32_e32 v191, 2, v191
	v_lshlrev_b32_e32 v249, 4, v4
	v_lshlrev_b32_e32 v248, 12, v4
	v_or_b32_e32 v248, v248, v191
	s_add_u32 s60, s18, s24
	s_addc_u32 s61, s19, s25
	v_readlane_b32 s68, v253, 11
	v_readlane_b32 s69, v253, 12
	global_load_dwordx4 v[134:137], v249, s[14:15]
	global_load_dwordx4 v[138:141], v249, s[14:15] offset:256
	global_load_dwordx4 v[142:145], v249, s[14:15] offset:512
	global_load_dwordx4 v[146:149], v249, s[14:15] offset:768
	global_load_dwordx4 v[150:153], v249, s[14:15] offset:2048
	global_load_dwordx4 v[154:157], v249, s[14:15] offset:2304
	global_load_dwordx4 v[158:161], v249, s[14:15] offset:2560
	global_load_dwordx4 v[162:165], v249, s[14:15] offset:2816
	global_load_dwordx4 v[224:227], v191, s[60:61]
	global_load_dwordx4 v[228:231], v191, s[60:61] offset:16
	global_load_dwordx4 v[232:235], v191, s[60:61] offset:512
	global_load_dwordx4 v[236:239], v191, s[60:61] offset:528
	global_load_dwordx4 v[192:195], v248, s[68:69]
	global_load_dwordx4 v[196:199], v248, s[68:69] offset:16
	global_load_dwordx4 v[200:203], v248, s[68:69] offset:512
	global_load_dwordx4 v[204:207], v248, s[68:69] offset:528
	v_add_u32_e32 v250, 0x10000, v248
	global_load_dwordx4 v[208:211], v250, s[68:69]
	global_load_dwordx4 v[212:215], v250, s[68:69] offset:16
	global_load_dwordx4 v[216:219], v250, s[68:69] offset:512
	global_load_dwordx4 v[220:223], v250, s[68:69] offset:528
	s_waitcnt vmcnt(12)
	v_add_f32_e32 v250, v135, v134
	v_add_f32_e32 v251, v136, v137
	v_add_f32_e32 v250, v250, v251
	v_fmamk_f32 v250, v250, 0x3b000000, v189
	v_mul_f32_e32 v251, 0x4f800000, v250
	v_cmp_gt_f32_e32 vcc, s57, v250
	s_nop 1
	v_cndmask_b32_e32 v250, v250, v251, vcc
	v_sqrt_f32_e32 v251, v250
	s_nop 0
	v_add_u32_e32 v252, -1, v251
	v_add_u32_e32 v240, 1, v251
	v_fma_f32 v134, -v252, v251, v250
	v_fma_f32 v135, -v240, v251, v250
	v_cmp_ge_f32_e64 s[62:63], 0, v134
	s_nop 1
	v_cndmask_b32_e64 v251, v251, v252, s[62:63]
	v_cmp_lt_f32_e64 s[62:63], 0, v135
	s_nop 1
	v_cndmask_b32_e64 v251, v251, v240, s[62:63]
	v_mul_f32_e32 v252, 0x37800000, v251
	v_cndmask_b32_e32 v251, v251, v252, vcc
	v_cmp_class_f32_e32 vcc, v250, v190
	s_nop 1
	v_cndmask_b32_e32 v250, v251, v250, vcc
	v_div_scale_f32 v251, s[62:63], v250, v250, 1.0
	v_rcp_f32_e32 v252, v251
	v_div_scale_f32 v134, vcc, 1.0, v250, 1.0
	v_fma_f32 v135, -v251, v252, 1.0
	v_fmac_f32_e32 v252, v135, v252
	v_mul_f32_e32 v135, v134, v252
	v_fma_f32 v136, -v251, v135, v134
	v_fmac_f32_e32 v135, v136, v252
	v_fma_f32 v251, -v251, v135, v134
	v_div_fmas_f32 v251, v251, v252, v135
	v_div_fixup_f32 v240, v251, v250, 1.0
	v_add_f32_e32 v250, v139, v138
	v_add_f32_e32 v251, v140, v141
	v_add_f32_e32 v250, v250, v251
	v_fmamk_f32 v250, v250, 0x3b000000, v189
	v_mul_f32_e32 v251, 0x4f800000, v250
	v_cmp_gt_f32_e32 vcc, s57, v250
	s_nop 1
	v_cndmask_b32_e32 v250, v250, v251, vcc
	v_sqrt_f32_e32 v251, v250
	s_nop 0
	v_add_u32_e32 v252, -1, v251
	v_add_u32_e32 v241, 1, v251
	v_fma_f32 v138, -v252, v251, v250
	v_fma_f32 v139, -v241, v251, v250
	v_cmp_ge_f32_e64 s[62:63], 0, v138
	s_nop 1
	v_cndmask_b32_e64 v251, v251, v252, s[62:63]
	v_cmp_lt_f32_e64 s[62:63], 0, v139
	s_nop 1
	v_cndmask_b32_e64 v251, v251, v241, s[62:63]
	v_mul_f32_e32 v252, 0x37800000, v251
	v_cndmask_b32_e32 v251, v251, v252, vcc
	v_cmp_class_f32_e32 vcc, v250, v190
	s_nop 1
	v_cndmask_b32_e32 v250, v251, v250, vcc
	v_div_scale_f32 v251, s[62:63], v250, v250, 1.0
	v_rcp_f32_e32 v252, v251
	v_div_scale_f32 v138, vcc, 1.0, v250, 1.0
	v_fma_f32 v139, -v251, v252, 1.0
	v_fmac_f32_e32 v252, v139, v252
	v_mul_f32_e32 v139, v138, v252
	v_fma_f32 v140, -v251, v139, v138
	v_fmac_f32_e32 v139, v140, v252
	v_fma_f32 v251, -v251, v139, v138
	v_div_fmas_f32 v251, v251, v252, v139
	v_div_fixup_f32 v241, v251, v250, 1.0
	v_add_f32_e32 v250, v143, v142
	v_add_f32_e32 v251, v144, v145
	v_add_f32_e32 v250, v250, v251
	v_fmamk_f32 v250, v250, 0x3b000000, v189
	v_mul_f32_e32 v251, 0x4f800000, v250
	v_cmp_gt_f32_e32 vcc, s57, v250
	s_nop 1
	v_cndmask_b32_e32 v250, v250, v251, vcc
	v_sqrt_f32_e32 v251, v250
	s_nop 0
	v_add_u32_e32 v252, -1, v251
	v_add_u32_e32 v242, 1, v251
	v_fma_f32 v142, -v252, v251, v250
	v_fma_f32 v143, -v242, v251, v250
	v_cmp_ge_f32_e64 s[62:63], 0, v142
	s_nop 1
	v_cndmask_b32_e64 v251, v251, v252, s[62:63]
	v_cmp_lt_f32_e64 s[62:63], 0, v143
	s_nop 1
	v_cndmask_b32_e64 v251, v251, v242, s[62:63]
	v_mul_f32_e32 v252, 0x37800000, v251
	v_cndmask_b32_e32 v251, v251, v252, vcc
	v_cmp_class_f32_e32 vcc, v250, v190
	s_nop 1
	v_cndmask_b32_e32 v250, v251, v250, vcc
	v_div_scale_f32 v251, s[62:63], v250, v250, 1.0
	v_rcp_f32_e32 v252, v251
	v_div_scale_f32 v142, vcc, 1.0, v250, 1.0
	v_fma_f32 v143, -v251, v252, 1.0
	v_fmac_f32_e32 v252, v143, v252
	v_mul_f32_e32 v143, v142, v252
	v_fma_f32 v144, -v251, v143, v142
	v_fmac_f32_e32 v143, v144, v252
	v_fma_f32 v251, -v251, v143, v142
	v_div_fmas_f32 v251, v251, v252, v143
	v_div_fixup_f32 v242, v251, v250, 1.0
	v_add_f32_e32 v250, v147, v146
	v_add_f32_e32 v251, v148, v149
	v_add_f32_e32 v250, v250, v251
	v_fmamk_f32 v250, v250, 0x3b000000, v189
	v_mul_f32_e32 v251, 0x4f800000, v250
	v_cmp_gt_f32_e32 vcc, s57, v250
	s_nop 1
	v_cndmask_b32_e32 v250, v250, v251, vcc
	v_sqrt_f32_e32 v251, v250
	s_nop 0
;     __device__ __forceinline__ void operator()(const pg8::f32x4 (&acc)[2][2][4][2], const pg8::Unit& u, int wr, int wc, int fr, int fq) const {
;     ...
;                 const int r = row0 + ai * 128 + m * 16;
;                 const int brow = r < NP ? 0 : 1 + ((r - NP) >> 3);
;                 const float* gt = mod + (size_t)brow * 6144 + 2048;
;                 const f32x4 s4 = *(const f32x4*)(SSM + (size_t)r * 4);
;                 const float ss = (s4[0] + s4[1]) + (s4[2] + s4[3]);
;                 const float rstd = 1.0f / sqrtf(ss * (1.f / 512.f) + EPS);
;                 const float* base = r < NP ? xp + (size_t)r * DM : xs + (size_t)(r - NP) * DM;
; #pragma unroll
;                 for (int bj = 0; bj < 2; ++bj) {
;                     const int col = colw + bj * 128;
;                     const f32x4 x0 = *(const f32x4*)(base + col), x1v = *(const f32x4*)(base + col + 4), g0 = *(const f32x4*)(gt + col) * rstd, g1 = *(const f32x4*)(gt + col + 4) * rstd;
	v_add_u32_e32 v252, -1, v251
	v_add_u32_e32 v243, 1, v251
	v_fma_f32 v146, -v252, v251, v250
	v_fma_f32 v147, -v243, v251, v250
	v_cmp_ge_f32_e64 s[62:63], 0, v146
	s_nop 1
	v_cndmask_b32_e64 v251, v251, v252, s[62:63]
	v_cmp_lt_f32_e64 s[62:63], 0, v147
	s_nop 1
	v_cndmask_b32_e64 v251, v251, v243, s[62:63]
	v_mul_f32_e32 v252, 0x37800000, v251
	v_cndmask_b32_e32 v251, v251, v252, vcc
	v_cmp_class_f32_e32 vcc, v250, v190
	s_nop 1
	v_cndmask_b32_e32 v250, v251, v250, vcc
	v_div_scale_f32 v251, s[62:63], v250, v250, 1.0
	v_rcp_f32_e32 v252, v251
	v_div_scale_f32 v146, vcc, 1.0, v250, 1.0
	v_fma_f32 v147, -v251, v252, 1.0
	v_fmac_f32_e32 v252, v147, v252
	v_mul_f32_e32 v147, v146, v252
	v_fma_f32 v148, -v251, v147, v146
	v_fmac_f32_e32 v147, v148, v252
	v_fma_f32 v251, -v251, v147, v146
	v_div_fmas_f32 v251, v251, v252, v147
	v_div_fixup_f32 v243, v251, v250, 1.0
	v_add_f32_e32 v250, v151, v150
	v_add_f32_e32 v251, v152, v153
	v_add_f32_e32 v250, v250, v251
	v_fmamk_f32 v250, v250, 0x3b000000, v189
	v_mul_f32_e32 v251, 0x4f800000, v250
	v_cmp_gt_f32_e32 vcc, s57, v250
	s_nop 1
	v_cndmask_b32_e32 v250, v250, v251, vcc
	v_sqrt_f32_e32 v251, v250
	s_nop 0
	v_add_u32_e32 v252, -1, v251
	v_add_u32_e32 v244, 1, v251
	v_fma_f32 v150, -v252, v251, v250
	v_fma_f32 v151, -v244, v251, v250
	v_cmp_ge_f32_e64 s[62:63], 0, v150
	s_nop 1
	v_cndmask_b32_e64 v251, v251, v252, s[62:63]
	v_cmp_lt_f32_e64 s[62:63], 0, v151
	s_nop 1
	v_cndmask_b32_e64 v251, v251, v244, s[62:63]
	v_mul_f32_e32 v252, 0x37800000, v251
	v_cndmask_b32_e32 v251, v251, v252, vcc
	v_cmp_class_f32_e32 vcc, v250, v190
	s_nop 1
	v_cndmask_b32_e32 v250, v251, v250, vcc
	v_div_scale_f32 v251, s[62:63], v250, v250, 1.0
	v_rcp_f32_e32 v252, v251
	v_div_scale_f32 v150, vcc, 1.0, v250, 1.0
	v_fma_f32 v151, -v251, v252, 1.0
	v_fmac_f32_e32 v252, v151, v252
	v_mul_f32_e32 v151, v150, v252
	v_fma_f32 v152, -v251, v151, v150
	v_fmac_f32_e32 v151, v152, v252
	v_fma_f32 v251, -v251, v151, v150
	v_div_fmas_f32 v251, v251, v252, v151
	v_div_fixup_f32 v244, v251, v250, 1.0
	v_add_f32_e32 v250, v155, v154
	v_add_f32_e32 v251, v156, v157
	v_add_f32_e32 v250, v250, v251
	v_fmamk_f32 v250, v250, 0x3b000000, v189
	v_mul_f32_e32 v251, 0x4f800000, v250
	v_cmp_gt_f32_e32 vcc, s57, v250
	s_nop 1
	v_cndmask_b32_e32 v250, v250, v251, vcc
	v_sqrt_f32_e32 v251, v250
	s_nop 0
	v_add_u32_e32 v252, -1, v251
	v_add_u32_e32 v245, 1, v251
	v_fma_f32 v154, -v252, v251, v250
	v_fma_f32 v155, -v245, v251, v250
	v_cmp_ge_f32_e64 s[62:63], 0, v154
	s_nop 1
	v_cndmask_b32_e64 v251, v251, v252, s[62:63]
	v_cmp_lt_f32_e64 s[62:63], 0, v155
	s_nop 1
	v_cndmask_b32_e64 v251, v251, v245, s[62:63]
	v_mul_f32_e32 v252, 0x37800000, v251
	v_cndmask_b32_e32 v251, v251, v252, vcc
	v_cmp_class_f32_e32 vcc, v250, v190
	s_nop 1
	v_cndmask_b32_e32 v250, v251, v250, vcc
	v_div_scale_f32 v251, s[62:63], v250, v250, 1.0
	v_rcp_f32_e32 v252, v251
	v_div_scale_f32 v154, vcc, 1.0, v250, 1.0
	v_fma_f32 v155, -v251, v252, 1.0
	v_fmac_f32_e32 v252, v155, v252
	v_mul_f32_e32 v155, v154, v252
	v_fma_f32 v156, -v251, v155, v154
	v_fmac_f32_e32 v155, v156, v252
	v_fma_f32 v251, -v251, v155, v154
	v_div_fmas_f32 v251, v251, v252, v155
	v_div_fixup_f32 v245, v251, v250, 1.0
	v_add_f32_e32 v250, v159, v158
	v_add_f32_e32 v251, v160, v161
	v_add_f32_e32 v250, v250, v251
	v_fmamk_f32 v250, v250, 0x3b000000, v189
	v_mul_f32_e32 v251, 0x4f800000, v250
	v_cmp_gt_f32_e32 vcc, s57, v250
	s_nop 1
	v_cndmask_b32_e32 v250, v250, v251, vcc
	v_sqrt_f32_e32 v251, v250
	s_nop 0
	v_add_u32_e32 v252, -1, v251
	v_add_u32_e32 v246, 1, v251
	v_fma_f32 v158, -v252, v251, v250
	v_fma_f32 v159, -v246, v251, v250
	v_cmp_ge_f32_e64 s[62:63], 0, v158
	s_nop 1
	v_cndmask_b32_e64 v251, v251, v252, s[62:63]
	v_cmp_lt_f32_e64 s[62:63], 0, v159
	s_nop 1
	v_cndmask_b32_e64 v251, v251, v246, s[62:63]
	v_mul_f32_e32 v252, 0x37800000, v251
	v_cndmask_b32_e32 v251, v251, v252, vcc
	v_cmp_class_f32_e32 vcc, v250, v190
	s_nop 1
	v_cndmask_b32_e32 v250, v251, v250, vcc
	v_div_scale_f32 v251, s[62:63], v250, v250, 1.0
	v_rcp_f32_e32 v252, v251
	v_div_scale_f32 v158, vcc, 1.0, v250, 1.0
	v_fma_f32 v159, -v251, v252, 1.0
	v_fmac_f32_e32 v252, v159, v252
	v_mul_f32_e32 v159, v158, v252
	v_fma_f32 v160, -v251, v159, v158
	v_fmac_f32_e32 v159, v160, v252
	v_fma_f32 v251, -v251, v159, v158
	v_div_fmas_f32 v251, v251, v252, v159
	v_div_fixup_f32 v246, v251, v250, 1.0
	v_add_f32_e32 v250, v163, v162
	v_add_f32_e32 v251, v164, v165
	v_add_f32_e32 v250, v250, v251
	v_fmamk_f32 v250, v250, 0x3b000000, v189
	v_mul_f32_e32 v251, 0x4f800000, v250
	v_cmp_gt_f32_e32 vcc, s57, v250
	s_nop 1
	v_cndmask_b32_e32 v250, v250, v251, vcc
	v_sqrt_f32_e32 v251, v250
	s_nop 0
	v_add_u32_e32 v252, -1, v251
	v_add_u32_e32 v247, 1, v251
	v_fma_f32 v162, -v252, v251, v250
	v_fma_f32 v163, -v247, v251, v250
	v_cmp_ge_f32_e64 s[62:63], 0, v162
	s_nop 1
	v_cndmask_b32_e64 v251, v251, v252, s[62:63]
	v_cmp_lt_f32_e64 s[62:63], 0, v163
	s_nop 1
	v_cndmask_b32_e64 v251, v251, v247, s[62:63]
	v_mul_f32_e32 v252, 0x37800000, v251
	v_cndmask_b32_e32 v251, v251, v252, vcc
	v_cmp_class_f32_e32 vcc, v250, v190
	s_nop 1
	v_cndmask_b32_e32 v250, v251, v250, vcc
	v_div_scale_f32 v251, s[62:63], v250, v250, 1.0
	v_rcp_f32_e32 v252, v251
	v_div_scale_f32 v162, vcc, 1.0, v250, 1.0
	v_fma_f32 v163, -v251, v252, 1.0
	v_fmac_f32_e32 v252, v163, v252
	v_mul_f32_e32 v163, v162, v252
	v_fma_f32 v164, -v251, v163, v162
	v_fmac_f32_e32 v163, v164, v252
	v_fma_f32 v251, -v251, v163, v162
	v_div_fmas_f32 v251, v251, v252, v163
	v_div_fixup_f32 v247, v251, v250, 1.0
	v_add_u32_e32 v250, 0x20000, v248
	global_load_dwordx4 v[134:137], v250, s[68:69]
	global_load_dwordx4 v[138:141], v250, s[68:69] offset:16
	global_load_dwordx4 v[142:145], v250, s[68:69] offset:512
	global_load_dwordx4 v[146:149], v250, s[68:69] offset:528
	v_add_u32_e32 v250, 0x30000, v248
	global_load_dwordx4 v[150:153], v250, s[68:69]
	global_load_dwordx4 v[154:157], v250, s[68:69] offset:16
	global_load_dwordx4 v[158:161], v250, s[68:69] offset:512
	global_load_dwordx4 v[162:165], v250, s[68:69] offset:528
	s_waitcnt vmcnt(8)
;     __device__ __forceinline__ void operator()(const pg8::f32x4 (&acc)[2][2][4][2], const pg8::Unit& u, int wr, int wc, int fr, int fq) const {
;     ...
;                 for (int bj = 0; bj < 2; ++bj) {
;                     const int col = colw + bj * 128;
;                     const f32x4 x0 = *(const f32x4*)(base + col), x1v = *(const f32x4*)(base + col + 4), g0 = *(const f32x4*)(gt + col) * rstd, g1 = *(const f32x4*)(gt + col + 4) * rstd;
;                     *(f32x4*)(x1 + (size_t)r * DM + col) = x0 + g0 * acc[ai][bj][m][0];
;                     *(f32x4*)(x1 + (size_t)r * DM + col + 4) = x1v + g1 * acc[ai][bj][m][1];
;                 }
	v_mul_f32_e32 v251, v224, v240
	v_fma_f32 v192, v130, v251, v192
	v_mul_f32_e32 v251, v225, v240
	v_fma_f32 v193, v131, v251, v193
	v_mul_f32_e32 v251, v226, v240
	v_fma_f32 v194, v132, v251, v194
	v_mul_f32_e32 v251, v227, v240
	v_fma_f32 v195, v133, v251, v195
	v_mul_f32_e32 v251, v228, v240
	v_fma_f32 v196, v126, v251, v196
	v_mul_f32_e32 v251, v229, v240
	v_fma_f32 v197, v127, v251, v197
	v_mul_f32_e32 v251, v230, v240
	v_fma_f32 v198, v128, v251, v198
	v_mul_f32_e32 v251, v231, v240
	v_fma_f32 v199, v129, v251, v199
	v_mul_f32_e32 v251, v232, v240
	v_fma_f32 v200, v98, v251, v200
	v_mul_f32_e32 v251, v233, v240
	v_fma_f32 v201, v99, v251, v201
	v_mul_f32_e32 v251, v234, v240
	v_fma_f32 v202, v100, v251, v202
	v_mul_f32_e32 v251, v235, v240
	v_fma_f32 v203, v101, v251, v203
	v_mul_f32_e32 v251, v236, v240
	v_fma_f32 v204, v94, v251, v204
	v_mul_f32_e32 v251, v237, v240
	v_fma_f32 v205, v95, v251, v205
	v_mul_f32_e32 v251, v238, v240
	v_fma_f32 v206, v96, v251, v206
	v_mul_f32_e32 v251, v239, v240
	v_fma_f32 v207, v97, v251, v207
	global_store_dwordx4 v248, v[192:195], s[16:17]
	global_store_dwordx4 v248, v[196:199], s[16:17] offset:16
	global_store_dwordx4 v248, v[200:203], s[16:17] offset:512
	global_store_dwordx4 v248, v[204:207], s[16:17] offset:528
	v_add_u32_e32 v250, 0x10000, v248
	v_mul_f32_e32 v251, v224, v241
	v_fma_f32 v208, v122, v251, v208
	v_mul_f32_e32 v251, v225, v241
	v_fma_f32 v209, v123, v251, v209
	v_mul_f32_e32 v251, v226, v241
	v_fma_f32 v210, v124, v251, v210
	v_mul_f32_e32 v251, v227, v241
	v_fma_f32 v211, v125, v251, v211
	v_mul_f32_e32 v251, v228, v241
	v_fma_f32 v212, v118, v251, v212
	v_mul_f32_e32 v251, v229, v241
	v_fma_f32 v213, v119, v251, v213
	v_mul_f32_e32 v251, v230, v241
	v_fma_f32 v214, v120, v251, v214
	v_mul_f32_e32 v251, v231, v241
	v_fma_f32 v215, v121, v251, v215
	v_mul_f32_e32 v251, v232, v241
	v_fma_f32 v216, v90, v251, v216
	v_mul_f32_e32 v251, v233, v241
	v_fma_f32 v217, v91, v251, v217
	v_mul_f32_e32 v251, v234, v241
	v_fma_f32 v218, v92, v251, v218
	v_mul_f32_e32 v251, v235, v241
	v_fma_f32 v219, v93, v251, v219
	v_mul_f32_e32 v251, v236, v241
	v_fma_f32 v220, v86, v251, v220
	v_mul_f32_e32 v251, v237, v241
	v_fma_f32 v221, v87, v251, v221
	v_mul_f32_e32 v251, v238, v241
	v_fma_f32 v222, v88, v251, v222
	v_mul_f32_e32 v251, v239, v241
	v_fma_f32 v223, v89, v251, v223
	global_store_dwordx4 v250, v[208:211], s[16:17]
	global_store_dwordx4 v250, v[212:215], s[16:17] offset:16
	global_store_dwordx4 v250, v[216:219], s[16:17] offset:512
	global_store_dwordx4 v250, v[220:223], s[16:17] offset:528
	s_nop 1
	v_add_u32_e32 v250, 0x80000, v248
	global_load_dwordx4 v[192:195], v250, s[68:69]
	global_load_dwordx4 v[196:199], v250, s[68:69] offset:16
	global_load_dwordx4 v[200:203], v250, s[68:69] offset:512
	global_load_dwordx4 v[204:207], v250, s[68:69] offset:528
	v_add_u32_e32 v250, 0x90000, v248
	global_load_dwordx4 v[208:211], v250, s[68:69]
	global_load_dwordx4 v[212:215], v250, s[68:69] offset:16
	global_load_dwordx4 v[216:219], v250, s[68:69] offset:512
	global_load_dwordx4 v[220:223], v250, s[68:69] offset:528
	s_waitcnt vmcnt(16)
	v_add_u32_e32 v250, 0x20000, v248
	v_mul_f32_e32 v251, v224, v242
	v_fma_f32 v134, v114, v251, v134
	v_mul_f32_e32 v251, v225, v242
	v_fma_f32 v135, v115, v251, v135
	v_mul_f32_e32 v251, v226, v242
	v_fma_f32 v136, v116, v251, v136
	v_mul_f32_e32 v251, v227, v242
	v_fma_f32 v137, v117, v251, v137
	v_mul_f32_e32 v251, v228, v242
	v_fma_f32 v138, v110, v251, v138
	v_mul_f32_e32 v251, v229, v242
	v_fma_f32 v139, v111, v251, v139
	v_mul_f32_e32 v251, v230, v242
	v_fma_f32 v140, v112, v251, v140
	v_mul_f32_e32 v251, v231, v242
	v_fma_f32 v141, v113, v251, v141
	v_mul_f32_e32 v251, v232, v242
	v_fma_f32 v142, v82, v251, v142
	v_mul_f32_e32 v251, v233, v242
	v_fma_f32 v143, v83, v251, v143
	v_mul_f32_e32 v251, v234, v242
	v_fma_f32 v144, v84, v251, v144
	v_mul_f32_e32 v251, v235, v242
	v_fma_f32 v145, v85, v251, v145
	v_mul_f32_e32 v251, v236, v242
	v_fma_f32 v146, v78, v251, v146
	v_mul_f32_e32 v251, v237, v242
	v_fma_f32 v147, v79, v251, v147
	v_mul_f32_e32 v251, v238, v242
	v_fma_f32 v148, v80, v251, v148
	v_mul_f32_e32 v251, v239, v242
	v_fma_f32 v149, v81, v251, v149
	global_store_dwordx4 v250, v[134:137], s[16:17]
	global_store_dwordx4 v250, v[138:141], s[16:17] offset:16
	global_store_dwordx4 v250, v[142:145], s[16:17] offset:512
	global_store_dwordx4 v250, v[146:149], s[16:17] offset:528
	v_add_u32_e32 v250, 0x30000, v248
	v_mul_f32_e32 v251, v224, v243
	v_fma_f32 v150, v106, v251, v150
	v_mul_f32_e32 v251, v225, v243
	v_fma_f32 v151, v107, v251, v151
	v_mul_f32_e32 v251, v226, v243
	v_fma_f32 v152, v108, v251, v152
	v_mul_f32_e32 v251, v227, v243
	v_fma_f32 v153, v109, v251, v153
	v_mul_f32_e32 v251, v228, v243
	v_fma_f32 v154, v102, v251, v154
	v_mul_f32_e32 v251, v229, v243
	v_fma_f32 v155, v103, v251, v155
	v_mul_f32_e32 v251, v230, v243
	v_fma_f32 v156, v104, v251, v156
	v_mul_f32_e32 v251, v231, v243
	v_fma_f32 v157, v105, v251, v157
	v_mul_f32_e32 v251, v232, v243
	v_fma_f32 v158, v74, v251, v158
	v_mul_f32_e32 v251, v233, v243
	v_fma_f32 v159, v75, v251, v159
	v_mul_f32_e32 v251, v234, v243
	v_fma_f32 v160, v76, v251, v160
	v_mul_f32_e32 v251, v235, v243
	v_fma_f32 v161, v77, v251, v161
	v_mul_f32_e32 v251, v236, v243
	v_fma_f32 v162, v70, v251, v162
	v_mul_f32_e32 v251, v237, v243
	v_fma_f32 v163, v71, v251, v163
	v_mul_f32_e32 v251, v238, v243
	v_fma_f32 v164, v72, v251, v164
	v_mul_f32_e32 v251, v239, v243
	v_fma_f32 v165, v73, v251, v165
	global_store_dwordx4 v250, v[150:153], s[16:17]
	global_store_dwordx4 v250, v[154:157], s[16:17] offset:16
	global_store_dwordx4 v250, v[158:161], s[16:17] offset:512
	global_store_dwordx4 v250, v[162:165], s[16:17] offset:528
	s_nop 1
	v_add_u32_e32 v250, 0xa0000, v248
	global_load_dwordx4 v[134:137], v250, s[68:69]
	global_load_dwordx4 v[138:141], v250, s[68:69] offset:16
	global_load_dwordx4 v[142:145], v250, s[68:69] offset:512
	global_load_dwordx4 v[146:149], v250, s[68:69] offset:528
	v_add_u32_e32 v250, 0xb0000, v248
	global_load_dwordx4 v[150:153], v250, s[68:69]
	global_load_dwordx4 v[154:157], v250, s[68:69] offset:16
	global_load_dwordx4 v[158:161], v250, s[68:69] offset:512
	global_load_dwordx4 v[162:165], v250, s[68:69] offset:528
	s_waitcnt vmcnt(16)
;     __device__ __forceinline__ void operator()(const pg8::f32x4 (&acc)[2][2][4][2], const pg8::Unit& u, int wr, int wc, int fr, int fq) const {
;     ...
;                 for (int bj = 0; bj < 2; ++bj) {
;                     const int col = colw + bj * 128;
;                     const f32x4 x0 = *(const f32x4*)(base + col), x1v = *(const f32x4*)(base + col + 4), g0 = *(const f32x4*)(gt + col) * rstd, g1 = *(const f32x4*)(gt + col + 4) * rstd;
;                     *(f32x4*)(x1 + (size_t)r * DM + col) = x0 + g0 * acc[ai][bj][m][0];
;                     *(f32x4*)(x1 + (size_t)r * DM + col + 4) = x1v + g1 * acc[ai][bj][m][1];
;                 }
	v_add_u32_e32 v250, 0x80000, v248
	v_mul_f32_e32 v251, v224, v244
	v_fma_f32 v192, v66, v251, v192
	v_mul_f32_e32 v251, v225, v244
	v_fma_f32 v193, v67, v251, v193
	v_mul_f32_e32 v251, v226, v244
	v_fma_f32 v194, v68, v251, v194
	v_mul_f32_e32 v251, v227, v244
	v_fma_f32 v195, v69, v251, v195
	v_mul_f32_e32 v251, v228, v244
	v_fma_f32 v196, v62, v251, v196
	v_mul_f32_e32 v251, v229, v244
	v_fma_f32 v197, v63, v251, v197
	v_mul_f32_e32 v251, v230, v244
	v_fma_f32 v198, v64, v251, v198
	v_mul_f32_e32 v251, v231, v244
	v_fma_f32 v199, v65, v251, v199
	v_mul_f32_e32 v251, v232, v244
	v_fma_f32 v200, v34, v251, v200
	v_mul_f32_e32 v251, v233, v244
	v_fma_f32 v201, v35, v251, v201
	v_mul_f32_e32 v251, v234, v244
	v_fma_f32 v202, v36, v251, v202
	v_mul_f32_e32 v251, v235, v244
	v_fma_f32 v203, v37, v251, v203
	v_mul_f32_e32 v251, v236, v244
	v_fma_f32 v204, v30, v251, v204
	v_mul_f32_e32 v251, v237, v244
	v_fma_f32 v205, v31, v251, v205
	v_mul_f32_e32 v251, v238, v244
	v_fma_f32 v206, v32, v251, v206
	v_mul_f32_e32 v251, v239, v244
	v_fma_f32 v207, v33, v251, v207
	global_store_dwordx4 v250, v[192:195], s[16:17]
	global_store_dwordx4 v250, v[196:199], s[16:17] offset:16
	global_store_dwordx4 v250, v[200:203], s[16:17] offset:512
	global_store_dwordx4 v250, v[204:207], s[16:17] offset:528
	v_add_u32_e32 v250, 0x90000, v248
	v_mul_f32_e32 v251, v224, v245
	v_fma_f32 v208, v58, v251, v208
	v_mul_f32_e32 v251, v225, v245
	v_fma_f32 v209, v59, v251, v209
	v_mul_f32_e32 v251, v226, v245
	v_fma_f32 v210, v60, v251, v210
	v_mul_f32_e32 v251, v227, v245
	v_fma_f32 v211, v61, v251, v211
	v_mul_f32_e32 v251, v228, v245
	v_fma_f32 v212, v54, v251, v212
	v_mul_f32_e32 v251, v229, v245
	v_fma_f32 v213, v55, v251, v213
	v_mul_f32_e32 v251, v230, v245
	v_fma_f32 v214, v56, v251, v214
	v_mul_f32_e32 v251, v231, v245
	v_fma_f32 v215, v57, v251, v215
	v_mul_f32_e32 v251, v232, v245
	v_fma_f32 v216, v26, v251, v216
	v_mul_f32_e32 v251, v233, v245
	v_fma_f32 v217, v27, v251, v217
	v_mul_f32_e32 v251, v234, v245
	v_fma_f32 v218, v28, v251, v218
	v_mul_f32_e32 v251, v235, v245
	v_fma_f32 v219, v29, v251, v219
	v_mul_f32_e32 v251, v236, v245
	v_fma_f32 v220, v22, v251, v220
	v_mul_f32_e32 v251, v237, v245
	v_fma_f32 v221, v23, v251, v221
	v_mul_f32_e32 v251, v238, v245
	v_fma_f32 v222, v24, v251, v222
	v_mul_f32_e32 v251, v239, v245
	v_fma_f32 v223, v25, v251, v223
	global_store_dwordx4 v250, v[208:211], s[16:17]
	global_store_dwordx4 v250, v[212:215], s[16:17] offset:16
	global_store_dwordx4 v250, v[216:219], s[16:17] offset:512
	global_store_dwordx4 v250, v[220:223], s[16:17] offset:528
	s_waitcnt vmcnt(8)
	v_add_u32_e32 v250, 0xa0000, v248
	v_mul_f32_e32 v251, v224, v246
	v_fma_f32 v134, v50, v251, v134
	v_mul_f32_e32 v251, v225, v246
	v_fma_f32 v135, v51, v251, v135
	v_mul_f32_e32 v251, v226, v246
	v_fma_f32 v136, v52, v251, v136
	v_mul_f32_e32 v251, v227, v246
	v_fma_f32 v137, v53, v251, v137
	v_mul_f32_e32 v251, v228, v246
	v_fma_f32 v138, v46, v251, v138
	v_mul_f32_e32 v251, v229, v246
	v_fma_f32 v139, v47, v251, v139
	v_mul_f32_e32 v251, v230, v246
	v_fma_f32 v140, v48, v251, v140
	v_mul_f32_e32 v251, v231, v246
	v_fma_f32 v141, v49, v251, v141
	v_mul_f32_e32 v251, v232, v246
	v_fma_f32 v142, v18, v251, v142
	v_mul_f32_e32 v251, v233, v246
	v_fma_f32 v143, v19, v251, v143
	v_mul_f32_e32 v251, v234, v246
	v_fma_f32 v144, v20, v251, v144
	v_mul_f32_e32 v251, v235, v246
	v_fma_f32 v145, v21, v251, v145
	v_mul_f32_e32 v251, v236, v246
	v_fma_f32 v146, v14, v251, v146
	v_mul_f32_e32 v251, v237, v246
	v_fma_f32 v147, v15, v251, v147
	v_mul_f32_e32 v251, v238, v246
	v_fma_f32 v148, v16, v251, v148
	v_mul_f32_e32 v251, v239, v246
	v_fma_f32 v149, v17, v251, v149
	global_store_dwordx4 v250, v[134:137], s[16:17]
	global_store_dwordx4 v250, v[138:141], s[16:17] offset:16
	global_store_dwordx4 v250, v[142:145], s[16:17] offset:512
	global_store_dwordx4 v250, v[146:149], s[16:17] offset:528
	v_add_u32_e32 v250, 0xb0000, v248
	v_mul_f32_e32 v251, v224, v247
	v_fma_f32 v150, v42, v251, v150
	v_mul_f32_e32 v251, v225, v247
	v_fma_f32 v151, v43, v251, v151
	v_mul_f32_e32 v251, v226, v247
	v_fma_f32 v152, v44, v251, v152
	v_mul_f32_e32 v251, v227, v247
	v_fma_f32 v153, v45, v251, v153
	v_mul_f32_e32 v251, v228, v247
	v_fma_f32 v154, v38, v251, v154
	v_mul_f32_e32 v251, v229, v247
	v_fma_f32 v155, v39, v251, v155
	v_mul_f32_e32 v251, v230, v247
	v_fma_f32 v156, v40, v251, v156
	v_mul_f32_e32 v251, v231, v247
	v_fma_f32 v157, v41, v251, v157
	v_mul_f32_e32 v251, v232, v247
	v_fma_f32 v158, v10, v251, v158
	v_mul_f32_e32 v251, v233, v247
	v_fma_f32 v159, v11, v251, v159
	v_mul_f32_e32 v251, v234, v247
	v_fma_f32 v160, v12, v251, v160
	v_mul_f32_e32 v251, v235, v247
	v_fma_f32 v161, v13, v251, v161
	v_mul_f32_e32 v251, v236, v247
	v_fma_f32 v162, v6, v251, v162
	v_mul_f32_e32 v251, v237, v247
	v_fma_f32 v163, v7, v251, v163
	v_mul_f32_e32 v251, v238, v247
	v_fma_f32 v164, v8, v251, v164
	v_mul_f32_e32 v251, v239, v247
	v_fma_f32 v165, v9, v251, v165
	global_store_dwordx4 v250, v[150:153], s[16:17]
	global_store_dwordx4 v250, v[154:157], s[16:17] offset:16
	global_store_dwordx4 v250, v[158:161], s[16:17] offset:512
	global_store_dwordx4 v250, v[162:165], s[16:17] offset:528
	s_branch .LBB0_1157
